# attention LongNet merge: second query tile's O loads issued together with the first (one exposed latency instead of two)
# baseline (speedup 1.0000x reference)
.LBB0_976:
	s_add_u32 s60, s96, s28
	s_addc_u32 s61, s97, 0
	v_lshl_add_u64 v[152:153], v[160:161], 1, s[60:61]
	s_mov_b64 s[60:61], 0xe000000
	v_lshl_add_u64 v[154:155], v[152:153], 0, s[60:61]
	s_mov_b64 s[60:61], 0x1a000000
	v_lshl_add_u64 v[206:207], v[150:151], 0, s[88:89]
	v_lshl_add_u64 v[152:153], v[152:153], 0, s[60:61]
	v_mad_u64_u32 v[184:185], s[60:61], v206, s20, v[154:155]
	v_mov_b32_e32 v182, v185
	v_lshlrev_b64 v[208:209], 6, v[206:207]
	v_mad_u64_u32 v[182:183], s[60:61], v207, s20, v[182:183]
	v_lshl_add_u64 v[208:209], s[46:47], 0, v[208:209]
	s_lshl_b32 s64, s24, 2
	v_mov_b32_e32 v185, v182
	v_lshl_add_u64 v[208:209], v[208:209], 0, s[64:65]
	global_load_dwordx2 v[214:215], v[184:185], off
	global_load_dwordx2 v[216:217], v[184:185], off offset:2048
	global_load_dwordx2 v[210:211], v[184:185], off offset:32
	global_load_dwordx2 v[212:213], v[184:185], off offset:2080
	global_load_dwordx2 v[202:203], v[184:185], off offset:64
	global_load_dwordx2 v[204:205], v[184:185], off offset:2112
	global_load_dwordx2 v[198:199], v[184:185], off offset:96
	global_load_dwordx2 v[200:201], v[184:185], off offset:2144
	global_load_dwordx2 v[194:195], v[184:185], off offset:128
	global_load_dwordx2 v[196:197], v[184:185], off offset:2176
	global_load_dwordx2 v[190:191], v[184:185], off offset:160
	global_load_dwordx2 v[192:193], v[184:185], off offset:2208
	global_load_dwordx2 v[186:187], v[184:185], off offset:192
	global_load_dwordx2 v[188:189], v[184:185], off offset:2240
	global_load_dwordx2 v[182:183], v[184:185], off offset:224
	s_nop 0
	global_load_dwordx2 v[184:185], v[184:185], off offset:2272
	s_nop 0
	global_load_dword v236, v[208:209], off
	s_nop 0
	global_load_dword v208, v[208:209], off offset:32
	v_lshlrev_b64 v[52:53], s23, v[148:149]
	v_lshl_add_u64 v[52:53], v[52:53], 0, s[88:89]
	v_mad_u64_u32 v[82:83], s[60:61], v52, s20, v[154:155]
	v_mov_b32_e32 v54, v83
	v_mad_u64_u32 v[54:55], s[60:61], v53, s20, v[54:55]
	v_mov_b32_e32 v83, v54
	global_load_dwordx2 v[52:53], v[82:83], off
	global_load_dwordx2 v[54:55], v[82:83], off offset:2048
	global_load_dwordx2 v[56:57], v[82:83], off offset:32
	global_load_dwordx2 v[58:59], v[82:83], off offset:2080
	global_load_dwordx2 v[60:61], v[82:83], off offset:64
	global_load_dwordx2 v[62:63], v[82:83], off offset:2112
	global_load_dwordx2 v[64:65], v[82:83], off offset:96
	global_load_dwordx2 v[66:67], v[82:83], off offset:2144
	global_load_dwordx2 v[68:69], v[82:83], off offset:128
	global_load_dwordx2 v[70:71], v[82:83], off offset:2176
	global_load_dwordx2 v[72:73], v[82:83], off offset:160
	global_load_dwordx2 v[74:75], v[82:83], off offset:2208
	global_load_dwordx2 v[76:77], v[82:83], off offset:192
	global_load_dwordx2 v[78:79], v[82:83], off offset:2240
	global_load_dwordx2 v[80:81], v[82:83], off offset:224
	global_load_dwordx2 v[82:83], v[82:83], off offset:2272
	v_div_scale_f32 v209, s[60:61], v246, v246, 1.0
	v_rcp_f32_e32 v237, v209
	v_lshlrev_b64 v[206:207], 11, v[206:207]
	v_lshl_add_u64 v[206:207], v[152:153], 0, v[206:207]
	v_fma_f32 v247, -v209, v237, 1.0
	v_fmac_f32_e32 v237, v247, v237
	v_div_scale_f32 v247, vcc, 1.0, v246, 1.0
	v_mul_f32_e32 v248, v247, v237
	v_fma_f32 v249, -v209, v248, v247
	v_fmac_f32_e32 v248, v249, v237
	v_fma_f32 v209, -v209, v248, v247
	v_div_fmas_f32 v209, v209, v237, v248
	v_div_fixup_f32 v237, v209, v246, 1.0
	v_log_f32_e32 v209, v246
	s_waitcnt vmcnt(0) lgkmcnt(0)
	v_and_b32_e32 v253, 0xffff0000, v214
	v_add_f32_e32 v247, s25, v209
	v_mul_f32_e32 v209, 0x3f317218, v247
	v_max3_f32 v248, v209, v236, v208
	v_sub_f32_e32 v208, v208, v248
	v_sub_f32_e32 v209, v236, v248
	v_mul_f32_e32 v208, 0x3fb8aa3b, v208
	v_mul_f32_e32 v209, 0x3fb8aa3b, v209
	v_exp_f32_e32 v236, v208
	v_fma_f32 v208, v247, s22, -v248
	v_exp_f32_e32 v209, v209
	v_mul_f32_e32 v208, 0x3fb8aa3b, v208
	v_exp_f32_e32 v208, v208
	v_add_f32_e32 v247, v209, v236
	v_add_f32_e32 v247, v208, v247
	v_div_scale_f32 v248, s[60:61], v247, v247, 1.0
	v_rcp_f32_e32 v249, v248
	s_nop 0
	v_fma_f32 v250, -v248, v249, 1.0
	v_fmac_f32_e32 v249, v250, v249
	v_div_scale_f32 v250, vcc, 1.0, v247, 1.0
	v_mul_f32_e32 v251, v250, v249
	v_fma_f32 v252, -v248, v251, v250
	v_fmac_f32_e32 v251, v252, v249
	v_fma_f32 v248, -v248, v251, v250
	v_div_fmas_f32 v248, v248, v249, v251
	v_div_fixup_f32 v249, v248, v247, 1.0
	v_mul_f32_e32 v248, v237, v249
	v_lshlrev_b32_e32 v251, 16, v214
	v_pk_mul_f32 v[208:209], v[208:209], v[248:249]
	v_mov_b32_e32 v250, v120
	v_mul_f32_e32 v247, v236, v249
	v_lshlrev_b32_e32 v236, 16, v216
	v_pk_mul_f32 v[248:249], v[208:209], v[250:251]
	v_mov_b32_e32 v252, v121
	v_fma_f32 v236, v247, v236, v249
	v_and_b32_e32 v214, 0xffff0000, v216
	v_add_f32_e32 v236, v248, v236
	v_pk_mul_f32 v[248:249], v[208:209], v[252:253]
	v_lshlrev_b32_e32 v237, 16, v215
	v_fma_f32 v214, v247, v214, v249
	v_add_f32_e32 v214, v248, v214
	v_cvt_pk_bf16_f32 v214, v236, v214
	v_mov_b32_e32 v236, v122
	v_lshlrev_b32_e32 v216, 16, v217
	v_pk_mul_f32 v[236:237], v[236:237], v[208:209]
	s_nop 0
	v_fma_f32 v216, v247, v216, v237
	v_add_f32_e32 v248, v236, v216
	v_and_b32_e32 v237, 0xffff0000, v215
	v_mov_b32_e32 v236, v123
	v_and_b32_e32 v215, 0xffff0000, v217
	v_pk_mul_f32 v[216:217], v[208:209], v[236:237]
	s_nop 0
	v_fma_f32 v215, v247, v215, v217
	v_add_f32_e32 v215, v216, v215
	v_cvt_pk_bf16_f32 v215, v248, v215
	global_store_dwordx2 v[206:207], v[214:215], off
	v_lshlrev_b32_e32 v215, 16, v210
	v_mov_b32_e32 v214, v116
	v_lshlrev_b32_e32 v216, 16, v212
	v_pk_mul_f32 v[214:215], v[208:209], v[214:215]
	s_nop 0
	v_fma_f32 v215, v247, v216, v215
	v_add_f32_e32 v216, v214, v215
	v_and_b32_e32 v215, 0xffff0000, v210
	v_mov_b32_e32 v214, v117
	v_and_b32_e32 v210, 0xffff0000, v212
	v_pk_mul_f32 v[214:215], v[208:209], v[214:215]
	v_lshlrev_b32_e32 v212, 16, v213
	v_fma_f32 v210, v247, v210, v215
	v_add_f32_e32 v210, v214, v210
	v_lshlrev_b32_e32 v215, 16, v211
	v_mov_b32_e32 v214, v118
	v_pk_mul_f32 v[214:215], v[208:209], v[214:215]
	v_cvt_pk_bf16_f32 v210, v216, v210
	s_nop 0
	v_fma_f32 v212, v247, v212, v215
	v_add_f32_e32 v216, v214, v212
	v_and_b32_e32 v215, 0xffff0000, v211
	v_mov_b32_e32 v214, v119
	v_and_b32_e32 v211, 0xffff0000, v213
	v_pk_mul_f32 v[212:213], v[208:209], v[214:215]
	s_nop 0
	v_fma_f32 v211, v247, v211, v213
	v_add_f32_e32 v211, v212, v211
	v_cvt_pk_bf16_f32 v211, v216, v211
	global_store_dwordx2 v[206:207], v[210:211], off offset:32
	v_lshlrev_b32_e32 v211, 16, v202
	v_mov_b32_e32 v210, v124
	v_lshlrev_b32_e32 v212, 16, v204
	v_pk_mul_f32 v[210:211], v[208:209], v[210:211]
	s_nop 0
	v_fma_f32 v211, v247, v212, v211
	v_add_f32_e32 v212, v210, v211
	v_and_b32_e32 v211, 0xffff0000, v202
	v_mov_b32_e32 v210, v125
	v_and_b32_e32 v202, 0xffff0000, v204
	v_pk_mul_f32 v[210:211], v[208:209], v[210:211]
	v_lshlrev_b32_e32 v204, 16, v205
	v_fma_f32 v202, v247, v202, v211
	v_add_f32_e32 v202, v210, v202
	v_lshlrev_b32_e32 v211, 16, v203
	v_mov_b32_e32 v210, v126
	v_pk_mul_f32 v[210:211], v[208:209], v[210:211]
	v_cvt_pk_bf16_f32 v202, v212, v202
	s_nop 0
	v_fma_f32 v204, v247, v204, v211
	v_add_f32_e32 v212, v210, v204
	v_and_b32_e32 v211, 0xffff0000, v203
	v_mov_b32_e32 v210, v127
	v_and_b32_e32 v203, 0xffff0000, v205
	v_pk_mul_f32 v[204:205], v[208:209], v[210:211]
	s_nop 0
	v_fma_f32 v203, v247, v203, v205
	v_add_f32_e32 v203, v204, v203
	v_cvt_pk_bf16_f32 v203, v212, v203
	global_store_dwordx2 v[206:207], v[202:203], off offset:64
	v_lshlrev_b32_e32 v203, 16, v198
	v_mov_b32_e32 v202, v132
	v_lshlrev_b32_e32 v204, 16, v200
	v_pk_mul_f32 v[202:203], v[208:209], v[202:203]
	s_nop 0
	v_fma_f32 v203, v247, v204, v203
	v_add_f32_e32 v204, v202, v203
	v_and_b32_e32 v203, 0xffff0000, v198
	v_mov_b32_e32 v202, v133
	v_and_b32_e32 v198, 0xffff0000, v200
	v_pk_mul_f32 v[202:203], v[208:209], v[202:203]
	v_lshlrev_b32_e32 v200, 16, v201
	v_fma_f32 v198, v247, v198, v203
	v_add_f32_e32 v198, v202, v198
	v_lshlrev_b32_e32 v203, 16, v199
	v_mov_b32_e32 v202, v134
	v_pk_mul_f32 v[202:203], v[208:209], v[202:203]
	v_cvt_pk_bf16_f32 v198, v204, v198
	s_nop 0
	v_fma_f32 v200, v247, v200, v203
	v_add_f32_e32 v204, v202, v200
	v_and_b32_e32 v203, 0xffff0000, v199
	v_mov_b32_e32 v202, v135
	v_and_b32_e32 v199, 0xffff0000, v201
	v_pk_mul_f32 v[200:201], v[208:209], v[202:203]
	s_nop 0
	v_fma_f32 v199, v247, v199, v201
	v_add_f32_e32 v199, v200, v199
	v_cvt_pk_bf16_f32 v199, v204, v199
	global_store_dwordx2 v[206:207], v[198:199], off offset:96
	v_lshlrev_b32_e32 v199, 16, v194
	v_mov_b32_e32 v198, v128
	v_lshlrev_b32_e32 v200, 16, v196
	v_pk_mul_f32 v[198:199], v[208:209], v[198:199]
	s_nop 0
	v_fma_f32 v199, v247, v200, v199
	v_add_f32_e32 v200, v198, v199
	v_and_b32_e32 v199, 0xffff0000, v194
	v_mov_b32_e32 v198, v129
	v_and_b32_e32 v194, 0xffff0000, v196
	v_pk_mul_f32 v[198:199], v[208:209], v[198:199]
	v_lshlrev_b32_e32 v196, 16, v197
	v_fma_f32 v194, v247, v194, v199
	v_add_f32_e32 v194, v198, v194
	v_lshlrev_b32_e32 v199, 16, v195
	v_mov_b32_e32 v198, v130
	v_pk_mul_f32 v[198:199], v[208:209], v[198:199]
	v_cvt_pk_bf16_f32 v194, v200, v194
	s_nop 0
	v_fma_f32 v196, v247, v196, v199
	v_add_f32_e32 v200, v198, v196
	v_and_b32_e32 v199, 0xffff0000, v195
	v_mov_b32_e32 v198, v131
	v_and_b32_e32 v195, 0xffff0000, v197
	v_pk_mul_f32 v[196:197], v[208:209], v[198:199]
	s_nop 0
	v_fma_f32 v195, v247, v195, v197
	v_add_f32_e32 v195, v196, v195
	v_cvt_pk_bf16_f32 v195, v200, v195
	global_store_dwordx2 v[206:207], v[194:195], off offset:128
	v_lshlrev_b32_e32 v195, 16, v190
	v_mov_b32_e32 v194, v136
	v_lshlrev_b32_e32 v196, 16, v192
	v_pk_mul_f32 v[194:195], v[208:209], v[194:195]
	s_nop 0
	v_fma_f32 v195, v247, v196, v195
	v_add_f32_e32 v196, v194, v195
	v_and_b32_e32 v195, 0xffff0000, v190
	v_mov_b32_e32 v194, v137
	v_and_b32_e32 v190, 0xffff0000, v192
	v_pk_mul_f32 v[194:195], v[208:209], v[194:195]
	v_lshlrev_b32_e32 v192, 16, v193
	v_fma_f32 v190, v247, v190, v195
	v_add_f32_e32 v190, v194, v190
	v_lshlrev_b32_e32 v195, 16, v191
	v_mov_b32_e32 v194, v138
	v_pk_mul_f32 v[194:195], v[208:209], v[194:195]
	v_cvt_pk_bf16_f32 v190, v196, v190
	s_nop 0
	v_fma_f32 v192, v247, v192, v195
	v_add_f32_e32 v196, v194, v192
	v_and_b32_e32 v195, 0xffff0000, v191
	v_mov_b32_e32 v194, v139
	v_and_b32_e32 v191, 0xffff0000, v193
	v_pk_mul_f32 v[192:193], v[208:209], v[194:195]
	s_nop 0
	v_fma_f32 v191, v247, v191, v193
	v_add_f32_e32 v191, v192, v191
	v_cvt_pk_bf16_f32 v191, v196, v191
	global_store_dwordx2 v[206:207], v[190:191], off offset:160
	v_lshlrev_b32_e32 v191, 16, v186
	v_mov_b32_e32 v190, v140
	v_lshlrev_b32_e32 v192, 16, v188
	v_pk_mul_f32 v[190:191], v[208:209], v[190:191]
	s_nop 0
	v_fma_f32 v191, v247, v192, v191
	v_add_f32_e32 v192, v190, v191
	v_and_b32_e32 v191, 0xffff0000, v186
	v_mov_b32_e32 v190, v141
	v_and_b32_e32 v186, 0xffff0000, v188
	v_pk_mul_f32 v[190:191], v[208:209], v[190:191]
	v_lshlrev_b32_e32 v188, 16, v189
	v_fma_f32 v186, v247, v186, v191
	v_add_f32_e32 v186, v190, v186
	v_lshlrev_b32_e32 v191, 16, v187
	v_mov_b32_e32 v190, v142
	v_pk_mul_f32 v[190:191], v[208:209], v[190:191]
	v_cvt_pk_bf16_f32 v186, v192, v186
	s_nop 0
	v_fma_f32 v188, v247, v188, v191
	v_add_f32_e32 v192, v190, v188
	v_and_b32_e32 v191, 0xffff0000, v187
	v_mov_b32_e32 v190, v143
	v_and_b32_e32 v187, 0xffff0000, v189
	v_pk_mul_f32 v[188:189], v[208:209], v[190:191]
	s_nop 0
	v_fma_f32 v187, v247, v187, v189
	v_add_f32_e32 v187, v188, v187
	v_cvt_pk_bf16_f32 v187, v192, v187
	global_store_dwordx2 v[206:207], v[186:187], off offset:192
	v_lshlrev_b32_e32 v187, 16, v182
	v_mov_b32_e32 v186, v144
	v_lshlrev_b32_e32 v188, 16, v184
	v_pk_mul_f32 v[186:187], v[208:209], v[186:187]
	s_nop 0
	v_fma_f32 v187, v247, v188, v187
	v_add_f32_e32 v188, v186, v187
	v_and_b32_e32 v187, 0xffff0000, v182
	v_mov_b32_e32 v186, v145
	v_and_b32_e32 v182, 0xffff0000, v184
	v_pk_mul_f32 v[186:187], v[208:209], v[186:187]
	v_lshlrev_b32_e32 v184, 16, v185
	v_fma_f32 v182, v247, v182, v187
	v_add_f32_e32 v182, v186, v182
	v_lshlrev_b32_e32 v187, 16, v183
	v_mov_b32_e32 v186, v146
	v_pk_mul_f32 v[186:187], v[208:209], v[186:187]
	v_cvt_pk_bf16_f32 v182, v188, v182
	s_nop 0
	v_fma_f32 v184, v247, v184, v187
	v_add_f32_e32 v188, v186, v184
	v_and_b32_e32 v187, 0xffff0000, v183
	v_mov_b32_e32 v186, v147
	v_and_b32_e32 v183, 0xffff0000, v185
	v_pk_mul_f32 v[184:185], v[208:209], v[186:187]
	s_nop 0
	v_fma_f32 v183, v247, v183, v185
	v_add_f32_e32 v183, v184, v183
	v_cvt_pk_bf16_f32 v183, v188, v183
	global_store_dwordx2 v[206:207], v[182:183], off offset:224
	v_lshlrev_b64 v[182:183], s23, v[148:149]
	v_lshl_add_u64 v[212:213], v[182:183], 0, s[88:89]
	v_lshlrev_b64 v[214:215], 6, v[212:213]
	v_lshl_add_u64 v[214:215], s[46:47], 0, v[214:215]
	v_lshl_add_u64 v[214:215], v[214:215], 0, s[64:65]
	v_mov_b32_e32 v208, v52
	v_mov_b32_e32 v209, v53
	v_mov_b32_e32 v210, v54
	v_mov_b32_e32 v211, v55
	v_mov_b32_e32 v204, v56
	v_mov_b32_e32 v205, v57
	v_mov_b32_e32 v206, v58
	v_mov_b32_e32 v207, v59
	v_mov_b32_e32 v200, v60
	v_mov_b32_e32 v201, v61
	v_mov_b32_e32 v202, v62
	v_mov_b32_e32 v203, v63
	v_mov_b32_e32 v196, v64
	v_mov_b32_e32 v197, v65
	v_mov_b32_e32 v198, v66
	v_mov_b32_e32 v199, v67
	v_mov_b32_e32 v192, v68
	v_mov_b32_e32 v193, v69
	v_mov_b32_e32 v194, v70
	v_mov_b32_e32 v195, v71
	v_mov_b32_e32 v188, v72
	v_mov_b32_e32 v189, v73
	v_mov_b32_e32 v190, v74
	v_mov_b32_e32 v191, v75
	v_mov_b32_e32 v184, v76
	v_mov_b32_e32 v185, v77
	v_mov_b32_e32 v186, v78
	v_mov_b32_e32 v187, v79
	v_mov_b32_e32 v154, v80
	v_mov_b32_e32 v155, v81
	s_nop 0
	v_mov_b32_e32 v182, v82
	v_mov_b32_e32 v183, v83
	s_nop 0
	global_load_dword v216, v[214:215], off
	s_nop 0
	global_load_dword v214, v[214:215], off offset:32
	v_div_scale_f32 v215, s[60:61], v167, v167, 1.0
	v_rcp_f32_e32 v217, v215
	v_lshlrev_b64 v[212:213], 11, v[212:213]
	v_lshl_add_u64 v[152:153], v[152:153], 0, v[212:213]
	v_fma_f32 v236, -v215, v217, 1.0
	v_fmac_f32_e32 v217, v236, v217
	v_div_scale_f32 v236, vcc, 1.0, v167, 1.0
	v_mul_f32_e32 v237, v236, v217
	v_fma_f32 v247, -v215, v237, v236
	v_fmac_f32_e32 v237, v247, v217
	v_fma_f32 v215, -v215, v237, v236
	v_div_fmas_f32 v215, v215, v217, v237
	v_div_fixup_f32 v236, v215, v167, 1.0
	v_log_f32_e32 v215, v167
	s_waitcnt vmcnt(0) lgkmcnt(0)
	v_lshlrev_b32_e32 v251, 16, v209
	v_add_f32_e32 v217, s25, v215
	v_mul_f32_e32 v215, 0x3f317218, v217
	v_max3_f32 v237, v215, v216, v214
	v_sub_f32_e32 v214, v214, v237
	v_sub_f32_e32 v215, v216, v237
	v_mul_f32_e32 v214, 0x3fb8aa3b, v214
	v_mul_f32_e32 v215, 0x3fb8aa3b, v215
	v_exp_f32_e32 v216, v214
	v_fma_f32 v214, v217, s22, -v237
	v_exp_f32_e32 v215, v215
	v_mul_f32_e32 v214, 0x3fb8aa3b, v214
	v_exp_f32_e32 v214, v214
	v_add_f32_e32 v217, v215, v216
	v_add_f32_e32 v217, v214, v217
	v_div_scale_f32 v237, s[60:61], v217, v217, 1.0
	v_rcp_f32_e32 v247, v237
	s_nop 0
	v_fma_f32 v248, -v237, v247, 1.0
	v_fmac_f32_e32 v247, v248, v247
	v_div_scale_f32 v248, vcc, 1.0, v217, 1.0
	v_mul_f32_e32 v249, v248, v247
	v_fma_f32 v250, -v237, v249, v248
	v_fmac_f32_e32 v249, v250, v247
	v_fma_f32 v237, -v237, v249, v248
	v_div_fmas_f32 v237, v237, v247, v249
	v_div_fixup_f32 v217, v237, v217, 1.0
	v_mul_f32_e32 v247, v216, v217
	v_mul_f32_e32 v216, v236, v217
	v_lshlrev_b32_e32 v237, 16, v208
	v_pk_mul_f32 v[212:213], v[214:215], v[216:217]
	v_mov_b32_e32 v236, v88
	v_lshlrev_b32_e32 v248, 16, v210
	v_pk_mul_f32 v[214:215], v[212:213], v[236:237]
	v_and_b32_e32 v249, 0xffff0000, v208
	v_fma_f32 v215, v247, v248, v215
	v_mov_b32_e32 v248, v89
	v_and_b32_e32 v208, 0xffff0000, v210
	v_add_f32_e32 v216, v214, v215
	v_pk_mul_f32 v[214:215], v[212:213], v[248:249]
	v_mov_b32_e32 v250, v90
	v_fma_f32 v208, v247, v208, v215
	v_lshlrev_b32_e32 v210, 16, v211
	v_add_f32_e32 v208, v214, v208
	v_pk_mul_f32 v[214:215], v[250:251], v[212:213]
	v_cvt_pk_bf16_f32 v208, v216, v208
	s_nop 0
	v_fma_f32 v210, v247, v210, v215
	v_add_f32_e32 v216, v214, v210
	v_and_b32_e32 v215, 0xffff0000, v209
	v_mov_b32_e32 v214, v91
	v_and_b32_e32 v209, 0xffff0000, v211
	v_pk_mul_f32 v[210:211], v[212:213], v[214:215]
	s_nop 0
	v_fma_f32 v209, v247, v209, v211
	v_add_f32_e32 v209, v210, v209
	v_cvt_pk_bf16_f32 v209, v216, v209
	global_store_dwordx2 v[152:153], v[208:209], off
	v_lshlrev_b32_e32 v209, 16, v204
	v_mov_b32_e32 v208, v84
	v_lshlrev_b32_e32 v210, 16, v206
	v_pk_mul_f32 v[208:209], v[212:213], v[208:209]
	s_nop 0
	v_fma_f32 v209, v247, v210, v209
	v_add_f32_e32 v210, v208, v209
	v_and_b32_e32 v209, 0xffff0000, v204
	v_mov_b32_e32 v208, v85
	v_and_b32_e32 v204, 0xffff0000, v206
	v_pk_mul_f32 v[208:209], v[212:213], v[208:209]
	v_lshlrev_b32_e32 v206, 16, v207
	v_fma_f32 v204, v247, v204, v209
	v_add_f32_e32 v204, v208, v204
	v_lshlrev_b32_e32 v209, 16, v205
	v_mov_b32_e32 v208, v86
	v_pk_mul_f32 v[208:209], v[212:213], v[208:209]
	v_cvt_pk_bf16_f32 v204, v210, v204
	s_nop 0
	v_fma_f32 v206, v247, v206, v209
	v_add_f32_e32 v210, v208, v206
	v_and_b32_e32 v209, 0xffff0000, v205
	v_mov_b32_e32 v208, v87
	v_and_b32_e32 v205, 0xffff0000, v207
	v_pk_mul_f32 v[206:207], v[212:213], v[208:209]
	s_nop 0
	v_fma_f32 v205, v247, v205, v207
	v_add_f32_e32 v205, v206, v205
	v_cvt_pk_bf16_f32 v205, v210, v205
	global_store_dwordx2 v[152:153], v[204:205], off offset:32
	v_lshlrev_b32_e32 v205, 16, v200
	v_mov_b32_e32 v204, v92
	v_lshlrev_b32_e32 v206, 16, v202
	v_pk_mul_f32 v[204:205], v[212:213], v[204:205]
	s_nop 0
	v_fma_f32 v205, v247, v206, v205
	v_add_f32_e32 v206, v204, v205
	v_and_b32_e32 v205, 0xffff0000, v200
	v_mov_b32_e32 v204, v93
	v_and_b32_e32 v200, 0xffff0000, v202
	v_pk_mul_f32 v[204:205], v[212:213], v[204:205]
	v_lshlrev_b32_e32 v202, 16, v203
	v_fma_f32 v200, v247, v200, v205
	v_add_f32_e32 v200, v204, v200
	v_lshlrev_b32_e32 v205, 16, v201
	v_mov_b32_e32 v204, v94
	v_pk_mul_f32 v[204:205], v[212:213], v[204:205]
	v_cvt_pk_bf16_f32 v200, v206, v200
	s_nop 0
	v_fma_f32 v202, v247, v202, v205
	v_add_f32_e32 v206, v204, v202
	v_and_b32_e32 v205, 0xffff0000, v201
	v_mov_b32_e32 v204, v95
	v_and_b32_e32 v201, 0xffff0000, v203
	v_pk_mul_f32 v[202:203], v[212:213], v[204:205]
	s_nop 0
	v_fma_f32 v201, v247, v201, v203
	v_add_f32_e32 v201, v202, v201
	v_cvt_pk_bf16_f32 v201, v206, v201
	global_store_dwordx2 v[152:153], v[200:201], off offset:64
	v_lshlrev_b32_e32 v201, 16, v196
	v_mov_b32_e32 v200, v100
	v_lshlrev_b32_e32 v202, 16, v198
	v_pk_mul_f32 v[200:201], v[212:213], v[200:201]
	s_nop 0
	v_fma_f32 v201, v247, v202, v201
	v_add_f32_e32 v202, v200, v201
	v_and_b32_e32 v201, 0xffff0000, v196
	v_mov_b32_e32 v200, v101
	v_and_b32_e32 v196, 0xffff0000, v198
	v_pk_mul_f32 v[200:201], v[212:213], v[200:201]
	v_lshlrev_b32_e32 v198, 16, v199
	v_fma_f32 v196, v247, v196, v201
	v_add_f32_e32 v196, v200, v196
	v_lshlrev_b32_e32 v201, 16, v197
	v_mov_b32_e32 v200, v102
	v_pk_mul_f32 v[200:201], v[212:213], v[200:201]
	v_cvt_pk_bf16_f32 v196, v202, v196
	s_nop 0
	v_fma_f32 v198, v247, v198, v201
	v_add_f32_e32 v202, v200, v198
	v_and_b32_e32 v201, 0xffff0000, v197
	v_mov_b32_e32 v200, v103
	v_and_b32_e32 v197, 0xffff0000, v199
	v_pk_mul_f32 v[198:199], v[212:213], v[200:201]
	s_nop 0
	v_fma_f32 v197, v247, v197, v199
	v_add_f32_e32 v197, v198, v197
	v_cvt_pk_bf16_f32 v197, v202, v197
	global_store_dwordx2 v[152:153], v[196:197], off offset:96
	v_lshlrev_b32_e32 v197, 16, v192
	v_mov_b32_e32 v196, v96
	v_lshlrev_b32_e32 v198, 16, v194
	v_pk_mul_f32 v[196:197], v[212:213], v[196:197]
	s_nop 0
	v_fma_f32 v197, v247, v198, v197
	v_add_f32_e32 v198, v196, v197
	v_and_b32_e32 v197, 0xffff0000, v192
	v_mov_b32_e32 v196, v97
	v_and_b32_e32 v192, 0xffff0000, v194
	v_pk_mul_f32 v[196:197], v[212:213], v[196:197]
	v_lshlrev_b32_e32 v194, 16, v195
	v_fma_f32 v192, v247, v192, v197
	v_add_f32_e32 v192, v196, v192
	v_lshlrev_b32_e32 v197, 16, v193
	v_mov_b32_e32 v196, v98
	v_pk_mul_f32 v[196:197], v[212:213], v[196:197]
	v_cvt_pk_bf16_f32 v192, v198, v192
	s_nop 0
	v_fma_f32 v194, v247, v194, v197
	v_add_f32_e32 v198, v196, v194
	v_and_b32_e32 v197, 0xffff0000, v193
	v_mov_b32_e32 v196, v99
	v_and_b32_e32 v193, 0xffff0000, v195
	v_pk_mul_f32 v[194:195], v[212:213], v[196:197]
	s_nop 0
	v_fma_f32 v193, v247, v193, v195
	v_add_f32_e32 v193, v194, v193
	v_cvt_pk_bf16_f32 v193, v198, v193
	global_store_dwordx2 v[152:153], v[192:193], off offset:128
	v_lshlrev_b32_e32 v193, 16, v188
	v_mov_b32_e32 v192, v104
	v_lshlrev_b32_e32 v194, 16, v190
	v_pk_mul_f32 v[192:193], v[212:213], v[192:193]
	s_nop 0
	v_fma_f32 v193, v247, v194, v193
	v_add_f32_e32 v194, v192, v193
	v_and_b32_e32 v193, 0xffff0000, v188
	v_mov_b32_e32 v192, v105
	v_and_b32_e32 v188, 0xffff0000, v190
	v_pk_mul_f32 v[192:193], v[212:213], v[192:193]
	v_lshlrev_b32_e32 v190, 16, v191
	v_fma_f32 v188, v247, v188, v193
	v_add_f32_e32 v188, v192, v188
	v_lshlrev_b32_e32 v193, 16, v189
	v_mov_b32_e32 v192, v106
	v_pk_mul_f32 v[192:193], v[212:213], v[192:193]
	v_cvt_pk_bf16_f32 v188, v194, v188
	s_nop 0
	v_fma_f32 v190, v247, v190, v193
	v_add_f32_e32 v194, v192, v190
	v_and_b32_e32 v193, 0xffff0000, v189
	v_mov_b32_e32 v192, v107
	v_and_b32_e32 v189, 0xffff0000, v191
	v_pk_mul_f32 v[190:191], v[212:213], v[192:193]
	s_nop 0
	v_fma_f32 v189, v247, v189, v191
	v_add_f32_e32 v189, v190, v189
	v_cvt_pk_bf16_f32 v189, v194, v189
	global_store_dwordx2 v[152:153], v[188:189], off offset:160
	v_lshlrev_b32_e32 v189, 16, v184
	v_mov_b32_e32 v188, v108
	v_lshlrev_b32_e32 v190, 16, v186
	v_pk_mul_f32 v[188:189], v[212:213], v[188:189]
	s_nop 0
	v_fma_f32 v189, v247, v190, v189
	v_add_f32_e32 v190, v188, v189
	v_and_b32_e32 v189, 0xffff0000, v184
	v_mov_b32_e32 v188, v109
	v_and_b32_e32 v184, 0xffff0000, v186
	v_pk_mul_f32 v[188:189], v[212:213], v[188:189]
	v_lshlrev_b32_e32 v186, 16, v187
	v_fma_f32 v184, v247, v184, v189
	v_add_f32_e32 v184, v188, v184
	v_lshlrev_b32_e32 v189, 16, v185
	v_mov_b32_e32 v188, v110
	v_pk_mul_f32 v[188:189], v[212:213], v[188:189]
	v_cvt_pk_bf16_f32 v184, v190, v184
	s_nop 0
	v_fma_f32 v186, v247, v186, v189
	v_add_f32_e32 v190, v188, v186
	v_and_b32_e32 v189, 0xffff0000, v185
	v_mov_b32_e32 v188, v111
	v_and_b32_e32 v185, 0xffff0000, v187
	v_pk_mul_f32 v[186:187], v[212:213], v[188:189]
	s_nop 0
	v_fma_f32 v185, v247, v185, v187
	v_add_f32_e32 v185, v186, v185
	v_cvt_pk_bf16_f32 v185, v190, v185
	global_store_dwordx2 v[152:153], v[184:185], off offset:192
	v_lshlrev_b32_e32 v185, 16, v154
	v_mov_b32_e32 v184, v112
	v_lshlrev_b32_e32 v186, 16, v182
	v_pk_mul_f32 v[184:185], v[212:213], v[184:185]
	s_nop 0
	v_fma_f32 v185, v247, v186, v185
	v_add_f32_e32 v186, v184, v185
	v_and_b32_e32 v185, 0xffff0000, v154
	v_mov_b32_e32 v184, v113
	v_and_b32_e32 v154, 0xffff0000, v182
	v_pk_mul_f32 v[184:185], v[212:213], v[184:185]
	v_lshlrev_b32_e32 v182, 16, v183
	v_fma_f32 v154, v247, v154, v185
	v_add_f32_e32 v154, v184, v154
	v_lshlrev_b32_e32 v185, 16, v155
	v_mov_b32_e32 v184, v114
	v_pk_mul_f32 v[184:185], v[212:213], v[184:185]
	v_cvt_pk_bf16_f32 v154, v186, v154
	s_nop 0
	v_fma_f32 v182, v247, v182, v185
	v_add_f32_e32 v186, v184, v182
	v_and_b32_e32 v185, 0xffff0000, v155
	v_mov_b32_e32 v184, v115
	v_and_b32_e32 v155, 0xffff0000, v183
	v_pk_mul_f32 v[182:183], v[212:213], v[184:185]
	s_nop 0
	v_fma_f32 v155, v247, v155, v183
	v_add_f32_e32 v155, v182, v155
	v_cvt_pk_bf16_f32 v155, v186, v155
	global_store_dwordx2 v[152:153], v[154:155], off offset:224
	s_cbranch_execnz .LBB0_975
